# barrier variant: the XCD leader's invalidate is issued right after its write-back/arrival and waited before its XCD is released (stricter ordering than the previous version)
# baseline (speedup 1.0000x reference)
; DEVINL unsigned xb_ld(unsigned* p) { return __hip_atomic_load(p, __ATOMIC_RELAXED, __HIP_MEMORY_SCOPE_AGENT); }
; DEVINL unsigned xb_add(unsigned* p, unsigned v) { return __hip_atomic_fetch_add(p, v, __ATOMIC_RELAXED, __HIP_MEMORY_SCOPE_AGENT); }
; #define XB_SPIN(cond, bar) do { unsigned _sp = 0; while (cond) { __builtin_amdgcn_s_sleep(1); \
;     if ((++_sp & 255u) == 0u) { if (xb_ld(&(bar)[XB_TMO])) break; if (_sp > XB_SPIN_CAP) { atomicAdd(&(bar)[XB_TMO], 1u); break; } } } } while (0)
; DEVINL void xcd_barrier(XcdBarrier& b) {
;     ...
;     if (old + 1u == (gen + 1u) * nloc) {
;       __builtin_amdgcn_fence(__ATOMIC_RELEASE, "agent");
;       asm volatile("s_waitcnt vmcnt(0)" ::: "memory");
;       const unsigned og = xb_add(&bar[XB_TOP], 1u);
;       const unsigned tg = og / nx;
;       if (og + 1u == (tg + 1u) * nx) xb_add(&bar[XB_TOPGEN], 1u);
;       else XB_SPIN(xb_ld(&bar[XB_TOPGEN]) == tg, bar);
;       __builtin_amdgcn_fence(__ATOMIC_ACQUIRE, "agent");
;       xb_add(&bar[XB_XGEN(b.x)], 1u);
.LBB0_59:
	s_or_b64 exec, exec, s[38:39]
	s_waitcnt vmcnt(0)
	global_atomic_add v[100:101], v115, off
	s_waitcnt vmcnt(0)

; DEVINL unsigned xb_ld(unsigned* p) { return __hip_atomic_load(p, __ATOMIC_RELAXED, __HIP_MEMORY_SCOPE_AGENT); }
; DEVINL unsigned xb_add(unsigned* p, unsigned v) { return __hip_atomic_fetch_add(p, v, __ATOMIC_RELAXED, __HIP_MEMORY_SCOPE_AGENT); }
; #define XB_SPIN(cond, bar) do { unsigned _sp = 0; while (cond) { __builtin_amdgcn_s_sleep(1); \
;     if ((++_sp & 255u) == 0u) { if (xb_ld(&(bar)[XB_TMO])) break; if (_sp > XB_SPIN_CAP) { atomicAdd(&(bar)[XB_TMO], 1u); break; } } } } while (0)
; DEVINL void xcd_barrier(XcdBarrier& b) {
;     ...
;       const unsigned og = xb_add(&bar[XB_TOP], 1u);
;       const unsigned tg = og / nx;
;       if (og + 1u == (tg + 1u) * nx) xb_add(&bar[XB_TOPGEN], 1u);
;       else XB_SPIN(xb_ld(&bar[XB_TOPGEN]) == tg, bar);
.LBB0_1584:
	s_or_b64 exec, exec, s[38:39]
	s_waitcnt vmcnt(0)
	v_readfirstlane_b32 s0, v3
	buffer_inv sc1
	v_sub_u32_e32 v4, 0, v96
	v_readlane_b32 s38, v192, 1
	v_add_u32_e32 v3, s0, v1
	v_cvt_f32_u32_e32 v1, v96
	v_readlane_b32 s39, v192, 2
	v_rcp_iflag_f32_e32 v1, v1
	s_nop 0
	v_mul_f32_e32 v1, 0x4f7ffffe, v1
	v_cvt_u32_f32_e32 v1, v1
	v_mul_lo_u32 v4, v4, v1
	v_mul_hi_u32 v4, v1, v4
	v_add_u32_e32 v1, v1, v4
	v_mul_hi_u32 v1, v3, v1
	v_mul_lo_u32 v4, v1, v96
	v_sub_u32_e32 v4, v3, v4
	v_cmp_ge_u32_e32 vcc, v4, v96
	v_add_u32_e32 v5, 1, v1
	v_add_u32_e32 v3, 1, v3
	v_cndmask_b32_e32 v1, v1, v5, vcc
	v_sub_u32_e32 v5, v4, v96
	v_cndmask_b32_e32 v4, v4, v5, vcc
	v_cmp_ge_u32_e32 vcc, v4, v96
	v_add_u32_e32 v4, 1, v1
	s_nop 0
	v_cndmask_b32_e32 v1, v1, v4, vcc
	v_mad_u64_u32 v[4:5], s[0:1], v96, v1, v[96:97]
	v_cmp_ne_u32_e32 vcc, v3, v4
	s_mov_b64 s[0:1], -1
	v_mov_b64_e32 v[4:5], s[38:39]
	s_and_saveexec_b64 s[38:39], vcc
	s_cbranch_execz .LBB0_1596
	v_readlane_b32 s0, v192, 1
	v_readlane_b32 s1, v192, 2
	s_nop 4
	global_load_dword v3, v2, s[0:1] sc1
	s_mov_b64 s[0:1], 0
	s_waitcnt vmcnt(0)
	v_cmp_eq_u32_e32 vcc, v3, v1
	s_and_saveexec_b64 s[40:41], vcc
	s_cbranch_execz .LBB0_1595
	s_mov_b32 s14, 1
	s_mov_b64 s[42:43], 0
	s_branch .LBB0_1588
